# mixer queue: first unit of each workgroup static (id = block index, no atomic), later fetches counter + grid size
# speedup vs baseline: 1.0106x; 1.0106x over previous
.LBB0_409:
	s_or_b64 exec, exec, s[0:1]
	s_mov_b32 s101, 1
	s_lshl_b32 s34, s97, 7
	s_lshl_b64 s[0:1], s[34:35], 2
	s_add_u32 s48, s14, s0
	s_addc_u32 s49, s15, s1
	s_lshl_b32 s2, s97, 8
	v_writelane_b32 v252, s2, 17
	s_lshl_b32 s3, s97, 9
	s_lshl_b32 s10, s97, 10
	v_writelane_b32 v252, s3, 18
	s_lshl_b32 s3, s97, 3
	s_add_u32 s6, s68, s0
	v_writelane_b32 v252, s3, 19
	s_addc_u32 s7, s69, s1
	v_writelane_b32 v252, s6, 20
	s_add_u32 s0, s70, s0
	s_addc_u32 s1, s71, s1
	v_writelane_b32 v252, s7, 21
	v_writelane_b32 v252, s0, 22
	s_mul_i32 s2, s97, 0x910000
	s_mul_i32 s4, s97, 0x4800
	v_writelane_b32 v252, s1, 23
	v_readlane_b32 s0, v253, 35
	s_add_u32 s0, s0, s2
	s_mov_b32 s5, s35
	v_writelane_b32 v252, s0, 24
	v_readlane_b32 s0, v253, 36
	s_addc_u32 s0, s0, 0
	s_mul_i32 s34, s97, 0x600
	v_writelane_b32 v252, s0, 25
	v_writelane_b32 v252, s4, 26
	s_add_u32 s11, s74, s4
	s_addc_u32 s96, s75, 0
	s_lshl_b64 s[0:1], s[34:35], 2
	s_add_u32 s84, s76, s0
	s_addc_u32 s85, s77, s1
	s_add_u32 s0, s14, s2
	s_addc_u32 s1, s15, 0
	v_writelane_b32 v252, s5, 27
	s_add_u32 s19, s0, 0xa108000
	s_addc_u32 s8, s1, 0
	v_writelane_b32 v252, s48, 28
	s_waitcnt lgkmcnt(0)
	s_barrier
	v_writelane_b32 v252, s49, 29
	s_branch .LBB0_413

.LBB0_413:
	v_mov_b32_e32 v130, v220
	s_nop 0
	v_cmp_eq_u32_e32 vcc, 0, v130
	s_barrier
	s_and_saveexec_b64 s[0:1], vcc
	s_cbranch_execz .LBB0_417
	s_mov_b64 s[4:5], exec
	v_mbcnt_lo_u32_b32 v1, s4, 0
	v_mbcnt_hi_u32_b32 v1, s5, v1
	v_cmp_eq_u32_e32 vcc, 0, v1
	s_and_saveexec_b64 s[2:3], vcc
	s_cbranch_execz .LBB0_416
	s_cmp_eq_u32 s101, 1
	s_cbranch_scc0 .Lsq_dyn
	s_mov_b32 s101, 0
	v_readlane_b32 s4, v252, 8
	s_nop 0
	v_mov_b32_e32 v2, s4
	s_branch .LBB0_416
.Lsq_dyn:
	s_bcnt1_i32_b64 s4, s[4:5]
	v_mov_b32_e32 v2, s4
	global_atomic_add v2, v0, v2, s[48:49] sc0
	v_readlane_b32 s4, v253, 6
	s_waitcnt vmcnt(0)
	v_add_u32_e32 v2, s4, v2
